# G2 merge GEMM: gate-tile loads issued one per MFMA in a dedicated copy of the kt%16==12 iteration (8 in each second half-step) instead of a 16-load burst
# speedup vs baseline: 1.0202x; 1.0027x over previous
.LBB0_409:
	s_add_i32 s38, s8, -3
	s_and_b32 s38, s38, 15
	s_cmp_eq_u32 s38, 12
	s_cbranch_scc1 .Lg2s_409
	s_add_i32 s17, s8, -3
	s_cmp_lt_u32 s17, 46
	s_cselect_b64 s[22:23], -1, 0
	s_and_b32 s38, s17, 15
	s_cmp_eq_u32 s38, 14
	s_cbranch_scc1 .Lg2_w2
	s_cmp_gt_u32 s17, 45
	s_cbranch_scc1 .Lg2_w0a
	s_waitcnt vmcnt(3)

.LBB0_415:
	s_waitcnt lgkmcnt(0)
	s_barrier
	s_add_i32 s19, s8, -2
	s_and_b32 s29, s19, 3
	s_mulk_i32 s29, 0x6000
	v_add_u32_e32 v127, s29, v235
	v_add_u32_e32 v131, s29, v236
	ds_read_b128 v[26:29], v131
	v_mfma_f32_16x16x32_bf16 v[90:93], v[14:17], v[106:109], v[90:93]
	ds_read_b128 v[18:21], v131 offset:1024
	v_mfma_f32_16x16x32_bf16 v[74:77], v[10:13], v[106:109], v[74:77]
	ds_read_b128 v[118:121], v127
	v_mfma_f32_16x16x32_bf16 v[58:61], v[6:9], v[106:109], v[58:61]
	ds_read_b128 v[114:117], v127 offset:1024
	v_mfma_f32_16x16x32_bf16 v[46:49], v[2:5], v[106:109], v[46:49]
	ds_read_b128 v[110:113], v127 offset:2048
	ds_read_b128 v[106:109], v127 offset:3072
	v_mfma_f32_16x16x32_bf16 v[94:97], v[14:17], v[242:245], v[94:97]
	v_mfma_f32_16x16x32_bf16 v[78:81], v[10:13], v[242:245], v[78:81]
	v_mfma_f32_16x16x32_bf16 v[62:65], v[6:9], v[242:245], v[62:65]
	v_mfma_f32_16x16x32_bf16 v[42:45], v[2:5], v[242:245], v[42:45]
	s_and_b32 s38, s17, 15
	s_cmp_eq_u32 s38, 14
	s_cbranch_scc1 .Lg2_w1
	s_and_b64 vcc, exec, s[24:25]
	s_cbranch_vccnz .Lg2_w0b
	s_waitcnt vmcnt(3)

.LBB0_423:
	v_mfma_f32_16x16x32_bf16 v[94:97], v[118:121], v[122:125], v[94:97]
	v_mfma_f32_16x16x32_bf16 v[78:81], v[114:117], v[122:125], v[78:81]
	v_mfma_f32_16x16x32_bf16 v[62:65], v[110:113], v[122:125], v[62:65]
	v_mfma_f32_16x16x32_bf16 v[42:45], v[106:109], v[122:125], v[42:45]
	s_and_b32 s19, s19, 15
	s_cmp_lg_u32 s19, 15
	s_cbranch_scc1 .LBB0_408
	s_waitcnt vmcnt(6)
	s_nop 7
	s_nop 7
	v_lshlrev_b32_e32 v106, 16, v22
	v_and_b32_e32 v107, 0xffff0000, v22
	v_pk_fma_f32 v[196:197], v[102:103], v[106:107], v[196:197]
	v_lshlrev_b32_e32 v108, 16, v23
	v_and_b32_e32 v109, 0xffff0000, v23
	v_pk_fma_f32 v[194:195], v[104:105], v[108:109], v[194:195]
	v_lshlrev_b32_e32 v106, 16, v24
	v_and_b32_e32 v107, 0xffff0000, v24
	v_pk_fma_f32 v[192:193], v[98:99], v[106:107], v[192:193]
	v_lshlrev_b32_e32 v108, 16, v25
	v_and_b32_e32 v109, 0xffff0000, v25
	v_pk_fma_f32 v[190:191], v[100:101], v[108:109], v[190:191]
	v_lshlrev_b32_e32 v106, 16, v30
	v_and_b32_e32 v107, 0xffff0000, v30
	v_pk_fma_f32 v[188:189], v[90:91], v[106:107], v[188:189]
	v_lshlrev_b32_e32 v108, 16, v31
	v_and_b32_e32 v109, 0xffff0000, v31
	v_pk_fma_f32 v[186:187], v[92:93], v[108:109], v[186:187]
	v_lshlrev_b32_e32 v106, 16, v32
	v_and_b32_e32 v107, 0xffff0000, v32
	v_pk_fma_f32 v[184:185], v[94:95], v[106:107], v[184:185]
	v_lshlrev_b32_e32 v108, 16, v33
	v_and_b32_e32 v109, 0xffff0000, v33
	v_pk_fma_f32 v[182:183], v[96:97], v[108:109], v[182:183]
	v_lshlrev_b32_e32 v106, 16, v34
	v_and_b32_e32 v107, 0xffff0000, v34
	v_pk_fma_f32 v[180:181], v[86:87], v[106:107], v[180:181]
	v_lshlrev_b32_e32 v108, 16, v35
	v_and_b32_e32 v109, 0xffff0000, v35
	v_pk_fma_f32 v[178:179], v[88:89], v[108:109], v[178:179]
	v_lshlrev_b32_e32 v106, 16, v36
	v_and_b32_e32 v107, 0xffff0000, v36
	v_pk_fma_f32 v[176:177], v[82:83], v[106:107], v[176:177]
	v_lshlrev_b32_e32 v108, 16, v37
	v_and_b32_e32 v109, 0xffff0000, v37
	v_pk_fma_f32 v[174:175], v[84:85], v[108:109], v[174:175]
	v_lshlrev_b32_e32 v106, 16, v38
	v_and_b32_e32 v107, 0xffff0000, v38
	v_pk_fma_f32 v[172:173], v[74:75], v[106:107], v[172:173]
	v_lshlrev_b32_e32 v108, 16, v39
	v_and_b32_e32 v109, 0xffff0000, v39
	v_pk_fma_f32 v[170:171], v[76:77], v[108:109], v[170:171]
	v_lshlrev_b32_e32 v106, 16, v40
	v_and_b32_e32 v107, 0xffff0000, v40
	v_pk_fma_f32 v[168:169], v[78:79], v[106:107], v[168:169]
	v_lshlrev_b32_e32 v108, 16, v41
	v_and_b32_e32 v109, 0xffff0000, v41
	v_pk_fma_f32 v[166:167], v[80:81], v[108:109], v[166:167]
	v_lshlrev_b32_e32 v106, 16, v246
	v_and_b32_e32 v107, 0xffff0000, v246
	v_pk_fma_f32 v[164:165], v[70:71], v[106:107], v[164:165]
	v_lshlrev_b32_e32 v108, 16, v247
	v_and_b32_e32 v109, 0xffff0000, v247
	v_pk_fma_f32 v[162:163], v[72:73], v[108:109], v[162:163]
	v_lshlrev_b32_e32 v106, 16, v248
	v_and_b32_e32 v107, 0xffff0000, v248
	v_pk_fma_f32 v[160:161], v[66:67], v[106:107], v[160:161]
	v_lshlrev_b32_e32 v108, 16, v249
	v_and_b32_e32 v109, 0xffff0000, v249
	v_pk_fma_f32 v[158:159], v[68:69], v[108:109], v[158:159]
	v_lshlrev_b32_e32 v106, 16, v250
	v_and_b32_e32 v107, 0xffff0000, v250
	v_pk_fma_f32 v[156:157], v[58:59], v[106:107], v[156:157]
	v_lshlrev_b32_e32 v108, 16, v251
	v_and_b32_e32 v109, 0xffff0000, v251
	v_pk_fma_f32 v[154:155], v[60:61], v[108:109], v[154:155]
	v_lshlrev_b32_e32 v106, 16, v238
	v_and_b32_e32 v107, 0xffff0000, v238
	v_pk_fma_f32 v[152:153], v[62:63], v[106:107], v[152:153]
	v_lshlrev_b32_e32 v108, 16, v239
	v_and_b32_e32 v109, 0xffff0000, v239
	v_pk_fma_f32 v[150:151], v[64:65], v[108:109], v[150:151]
	v_lshlrev_b32_e32 v106, 16, v240
	v_and_b32_e32 v107, 0xffff0000, v240
	v_pk_fma_f32 v[148:149], v[54:55], v[106:107], v[148:149]
	v_lshlrev_b32_e32 v108, 16, v241
	v_and_b32_e32 v109, 0xffff0000, v241
	v_pk_fma_f32 v[146:147], v[56:57], v[108:109], v[146:147]
	v_lshlrev_b32_e32 v106, 16, v132
	v_and_b32_e32 v107, 0xffff0000, v132
	v_pk_fma_f32 v[144:145], v[50:51], v[106:107], v[144:145]
	v_lshlrev_b32_e32 v108, 16, v133
	v_and_b32_e32 v109, 0xffff0000, v133
	v_pk_fma_f32 v[142:143], v[52:53], v[108:109], v[142:143]
	v_lshlrev_b32_e32 v106, 16, v198
	v_and_b32_e32 v107, 0xffff0000, v198
	v_pk_fma_f32 v[140:141], v[46:47], v[106:107], v[140:141]
	v_lshlrev_b32_e32 v108, 16, v199
	v_and_b32_e32 v109, 0xffff0000, v199
	v_pk_fma_f32 v[138:139], v[48:49], v[108:109], v[138:139]
	v_lshlrev_b32_e32 v106, 16, v226
	v_and_b32_e32 v107, 0xffff0000, v226
	v_pk_fma_f32 v[136:137], v[42:43], v[106:107], v[136:137]
	v_lshlrev_b32_e32 v108, 16, v227
	v_and_b32_e32 v109, 0xffff0000, v227
	v_pk_fma_f32 v[134:135], v[44:45], v[108:109], v[134:135]
	v_mov_b32_e32 v42, 0
	v_mov_b32_e32 v43, v42
	v_mov_b32_e32 v44, v42
	v_mov_b32_e32 v45, v42
	v_mov_b32_e32 v46, v42
	v_mov_b32_e32 v47, v42
	v_mov_b32_e32 v48, v42
	v_mov_b32_e32 v49, v42
	v_mov_b32_e32 v50, v42
	v_mov_b32_e32 v51, v42
	v_mov_b32_e32 v52, v42
	v_mov_b32_e32 v53, v42
	v_mov_b32_e32 v54, v42
	v_mov_b32_e32 v55, v42
	v_mov_b32_e32 v56, v42
	v_mov_b32_e32 v57, v42
	v_mov_b32_e32 v62, v42
	v_mov_b32_e32 v63, v42
	v_mov_b32_e32 v64, v42
	v_mov_b32_e32 v65, v42
	v_mov_b32_e32 v58, v42
	v_mov_b32_e32 v59, v42
	v_mov_b32_e32 v60, v42
	v_mov_b32_e32 v61, v42
	v_mov_b32_e32 v66, v42
	v_mov_b32_e32 v67, v42
	v_mov_b32_e32 v68, v42
	v_mov_b32_e32 v69, v42
	v_mov_b32_e32 v70, v42
	v_mov_b32_e32 v71, v42
	v_mov_b32_e32 v72, v42
	v_mov_b32_e32 v73, v42
	v_mov_b32_e32 v78, v42
	v_mov_b32_e32 v79, v42
	v_mov_b32_e32 v80, v42
	v_mov_b32_e32 v81, v42
	v_mov_b32_e32 v74, v42
	v_mov_b32_e32 v75, v42
	v_mov_b32_e32 v76, v42
	v_mov_b32_e32 v77, v42
	v_mov_b32_e32 v82, v42
	v_mov_b32_e32 v83, v42
	v_mov_b32_e32 v84, v42
	v_mov_b32_e32 v85, v42
	v_mov_b32_e32 v86, v42
	v_mov_b32_e32 v87, v42
	v_mov_b32_e32 v88, v42
	v_mov_b32_e32 v89, v42
	v_mov_b32_e32 v94, v42
	v_mov_b32_e32 v95, v42
	v_mov_b32_e32 v96, v42
	v_mov_b32_e32 v97, v42
	v_mov_b32_e32 v90, v42
	v_mov_b32_e32 v91, v42
	v_mov_b32_e32 v92, v42
	v_mov_b32_e32 v93, v42
	v_mov_b32_e32 v98, v42
	v_mov_b32_e32 v99, v42
	v_mov_b32_e32 v100, v42
	v_mov_b32_e32 v101, v42
	v_mov_b32_e32 v102, v42
	v_mov_b32_e32 v103, v42
	v_mov_b32_e32 v104, v42
	v_mov_b32_e32 v105, v42
	s_branch .LBB0_408

.Lg2_w1:
	s_and_b64 vcc, exec, s[24:25]
	s_cbranch_vccnz .Lg2_w0b
	s_waitcnt vmcnt(11)
	s_branch .LBB0_419

.Lg2s_409:
	s_add_i32 s17, s8, -3
	s_cmp_lt_u32 s17, 46
	s_cselect_b64 s[22:23], -1, 0
	s_waitcnt vmcnt(3)
.Lg2s_413:
	s_waitcnt lgkmcnt(0)
	s_cmp_gt_u32 s17, 44
	s_cselect_b64 s[24:25], -1, 0
	s_and_b64 vcc, exec, s[24:25]
	s_barrier
	s_and_b32 s28, s17, 2
	s_mulk_i32 s28, 0x6000
	v_add_u32_e32 v110, s28, v237
	ds_read_b128 v[106:109], v110
	ds_read_b128 v[242:245], v110 offset:1024
	s_cbranch_vccnz .Lgm_G2x_nodma0
	s_and_b32 s89, s8, 3
	s_mulk_i32 s89, 0x6000
	s_add_i32 s89, s89, s88
	s_mov_b32 m0, s89
	v_mfma_f32_16x16x32_bf16 v[102:105], v[14:17], v[26:29], v[102:105]
	v_mfma_f32_16x16x32_bf16 v[86:89], v[10:13], v[26:29], v[86:89]
	global_load_lds_dwordx4 v126, s[90:91]
	s_add_i32 m0, s89, 0x2000
	v_mfma_f32_16x16x32_bf16 v[70:73], v[6:9], v[26:29], v[70:73]
	v_mfma_f32_16x16x32_bf16 v[54:57], v[2:5], v[26:29], v[54:57]
	global_load_lds_dwordx4 v128, s[90:91]
	s_add_i32 m0, s89, 0x4000
	v_mfma_f32_16x16x32_bf16 v[98:101], v[14:17], v[18:21], v[98:101]
	v_mfma_f32_16x16x32_bf16 v[82:85], v[10:13], v[18:21], v[82:85]
	global_load_lds_dwordx4 v130, s[92:93]
	v_mfma_f32_16x16x32_bf16 v[66:69], v[6:9], v[18:21], v[66:69]
	v_mfma_f32_16x16x32_bf16 v[50:53], v[2:5], v[18:21], v[50:53]
	s_add_u32 s90, s90, 64
	s_addc_u32 s91, s91, 0
	s_add_u32 s92, s92, 64
	s_addc_u32 s93, s93, 0
	s_lshr_b32 s94, s17, 4
	s_lshl_b32 s94, s94, 15
	s_add_u32 s94, s36, s94
	s_addc_u32 s95, s37, 0
.Lg2s_415:
	s_waitcnt lgkmcnt(0)
	s_barrier
	s_add_i32 s19, s8, -2
	s_and_b32 s29, s19, 3
	s_mulk_i32 s29, 0x6000
	v_add_u32_e32 v127, s29, v235
	v_add_u32_e32 v131, s29, v236
	ds_read_b128 v[26:29], v131
	v_mfma_f32_16x16x32_bf16 v[90:93], v[14:17], v[106:109], v[90:93]
	global_load_dwordx2 v[22:23], v0, s[94:95] nt
	ds_read_b128 v[18:21], v131 offset:1024
	v_mfma_f32_16x16x32_bf16 v[74:77], v[10:13], v[106:109], v[74:77]
	global_load_dwordx2 v[24:25], v0, s[94:95] offset:512 nt
	ds_read_b128 v[118:121], v127
	v_mfma_f32_16x16x32_bf16 v[58:61], v[6:9], v[106:109], v[58:61]
	global_load_dwordx2 v[30:31], v0, s[94:95] offset:1024 nt
	ds_read_b128 v[114:117], v127 offset:1024
	v_mfma_f32_16x16x32_bf16 v[46:49], v[2:5], v[106:109], v[46:49]
	global_load_dwordx2 v[32:33], v0, s[94:95] offset:1536 nt
	ds_read_b128 v[110:113], v127 offset:2048
	ds_read_b128 v[106:109], v127 offset:3072
	v_mfma_f32_16x16x32_bf16 v[94:97], v[14:17], v[242:245], v[94:97]
	s_add_u32 s94, s94, 0x18000
	s_addc_u32 s95, s95, 0
	global_load_dwordx2 v[34:35], v0, s[94:95] nt
	v_mfma_f32_16x16x32_bf16 v[78:81], v[10:13], v[242:245], v[78:81]
	global_load_dwordx2 v[36:37], v0, s[94:95] offset:512 nt
	v_mfma_f32_16x16x32_bf16 v[62:65], v[6:9], v[242:245], v[62:65]
	global_load_dwordx2 v[38:39], v0, s[94:95] offset:1024 nt
	v_mfma_f32_16x16x32_bf16 v[42:45], v[2:5], v[242:245], v[42:45]
	global_load_dwordx2 v[40:41], v0, s[94:95] offset:1536 nt
	s_waitcnt vmcnt(11)

.Lg2s_421:
	s_waitcnt lgkmcnt(0)
	s_barrier
	v_mfma_f32_16x16x32_bf16 v[90:93], v[118:121], v[242:245], v[90:93]
	s_add_u32 s94, s94, 0x18000
	s_addc_u32 s95, s95, 0
	global_load_dwordx2 v[246:247], v0, s[94:95] nt
	v_mfma_f32_16x16x32_bf16 v[74:77], v[114:117], v[242:245], v[74:77]
	global_load_dwordx2 v[248:249], v0, s[94:95] offset:512 nt
	v_mfma_f32_16x16x32_bf16 v[58:61], v[110:113], v[242:245], v[58:61]
	global_load_dwordx2 v[250:251], v0, s[94:95] offset:1024 nt
	v_mfma_f32_16x16x32_bf16 v[46:49], v[106:109], v[242:245], v[46:49]
	global_load_dwordx2 v[238:239], v0, s[94:95] offset:1536 nt
	s_andn2_b64 vcc, exec, s[22:23]
	s_cbranch_vccnz .Lg2s_423
	s_add_i32 s22, s8, -1
	s_and_b32 s22, s22, 2
	s_mulk_i32 s22, 0x6000
	v_add_u32_e32 v18, s22, v235
	ds_read_b128 v[14:17], v18
	ds_read_b128 v[10:13], v18 offset:1024
	ds_read_b128 v[6:9], v18 offset:2048
	ds_read_b128 v[2:5], v18 offset:3072
	v_add_u32_e32 v129, s22, v236
	ds_read_b128 v[26:29], v129
	ds_read_b128 v[18:21], v129 offset:1024
.Lg2s_423:
	v_mfma_f32_16x16x32_bf16 v[94:97], v[118:121], v[122:125], v[94:97]
	s_add_u32 s94, s94, 0x18000
	s_addc_u32 s95, s95, 0
	global_load_dwordx2 v[240:241], v0, s[94:95] nt
	v_mfma_f32_16x16x32_bf16 v[78:81], v[114:117], v[122:125], v[78:81]
	global_load_dwordx2 v[132:133], v0, s[94:95] offset:512 nt
	v_mfma_f32_16x16x32_bf16 v[62:65], v[110:113], v[122:125], v[62:65]
	global_load_dwordx2 v[198:199], v0, s[94:95] offset:1024 nt
	v_mfma_f32_16x16x32_bf16 v[42:45], v[106:109], v[122:125], v[42:45]
	global_load_dwordx2 v[226:227], v0, s[94:95] offset:1536 nt
	s_branch .LBB0_408
.Lg2s_nodma1:
	v_mfma_f32_16x16x32_bf16 v[102:105], v[118:121], v[26:29], v[102:105]
	v_mfma_f32_16x16x32_bf16 v[86:89], v[114:117], v[26:29], v[86:89]
	v_mfma_f32_16x16x32_bf16 v[70:73], v[110:113], v[26:29], v[70:73]
	v_mfma_f32_16x16x32_bf16 v[54:57], v[106:109], v[26:29], v[54:57]
	v_mfma_f32_16x16x32_bf16 v[98:101], v[118:121], v[18:21], v[98:101]
	v_mfma_f32_16x16x32_bf16 v[82:85], v[114:117], v[18:21], v[82:85]
	v_mfma_f32_16x16x32_bf16 v[66:69], v[110:113], v[18:21], v[66:69]
	v_mfma_f32_16x16x32_bf16 v[50:53], v[106:109], v[18:21], v[50:53]
	s_branch .Lg2s_421
.LBB0_425:
	v_cmp_gt_i32_e32 vcc, 4, v230
	s_and_saveexec_b64 s[20:21], vcc
	s_cbranch_execz .LBB0_427
	s_barrier
